# PVo: out-proj GEMM processes the workgroup's two tiles (mt, mt+8; same nt) as one pair sharing B fragments (6 LDS-DMA pieces per 16 MFMAs); epilogue lane constants recomputed after the k-loop
# speedup vs baseline: 1.0041x; 1.0041x over previous
.LBB0_993:
	s_nop 15
	s_nop 7
	v_add_u32_e32 v0, 0x800, v125
	ds_write2_b32 v125, v50, v34 offset1:32
	ds_write2_b32 v125, v51, v35 offset0:64 offset1:96
	ds_write2_b32 v125, v52, v36 offset0:128 offset1:160
	ds_write2_b32 v125, v53, v37 offset0:192 offset1:224
	ds_write2_b32 v0, v54, v38 offset1:32
	ds_write2_b32 v0, v55, v39 offset0:64 offset1:96
	ds_write2_b32 v0, v56, v40 offset0:128 offset1:160
	ds_write2_b32 v0, v57, v41 offset0:192 offset1:224
	v_add_u32_e32 v0, 0x1000, v125
	s_lshl_b32 s4, s4, 7
	ds_write2_b32 v0, v58, v42 offset1:32
	ds_write2_b32 v0, v59, v43 offset0:64 offset1:96
	ds_write2_b32 v0, v60, v44 offset0:128 offset1:160
	ds_write2_b32 v0, v61, v45 offset0:192 offset1:224
	v_add_u32_e32 v0, 0x1800, v125
	s_lshl_b64 s[6:7], s[6:7], 17
	s_ashr_i32 s5, s4, 31
	ds_write2_b32 v0, v62, v46 offset1:32
	ds_write2_b32 v0, v63, v47 offset0:64 offset1:96
	ds_write2_b32 v0, v64, v48 offset0:128 offset1:160
	ds_write2_b32 v0, v65, v49 offset0:192 offset1:224
	v_add_u32_e32 v0, 0x2000, v125
	s_add_u32 s4, s4, s6
	ds_write2_b32 v0, v18, v2 offset1:32
	ds_write2_b32 v0, v19, v3 offset0:64 offset1:96
	ds_write2_b32 v0, v20, v4 offset0:128 offset1:160
	ds_write2_b32 v0, v21, v5 offset0:192 offset1:224
	v_add_u32_e32 v0, 0x2800, v125
	s_addc_u32 s5, s5, s7
	ds_write2_b32 v0, v22, v6 offset1:32
	ds_write2_b32 v0, v23, v7 offset0:64 offset1:96
	ds_write2_b32 v0, v24, v8 offset0:128 offset1:160
	ds_write2_b32 v0, v25, v9 offset0:192 offset1:224
	v_add_u32_e32 v0, 0x3000, v125
	v_lshl_add_u64 v[2:3], s[4:5], 0, v[66:67]
	ds_write2_b32 v0, v26, v10 offset1:32
	ds_write2_b32 v0, v27, v11 offset0:64 offset1:96
	ds_write2_b32 v0, v28, v12 offset0:128 offset1:160
	ds_write2_b32 v0, v29, v13 offset0:192 offset1:224
	v_add_u32_e32 v0, 0x3800, v125
	v_lshlrev_b64 v[108:109], 2, v[2:3]
	ds_write2_b32 v0, v30, v14 offset1:32
	ds_write2_b32 v0, v31, v15 offset0:64 offset1:96
	ds_write2_b32 v0, v32, v16 offset0:128 offset1:160
	ds_write2_b32 v0, v33, v17 offset0:192 offset1:224
	v_lshl_add_u64 v[2:3], v[68:69], 0, v[108:109]
	global_load_dwordx4 v[54:57], v[2:3], off
	v_add_co_u32_e32 v4, vcc, s3, v2
	s_mov_b32 s4, 0x8000
	s_nop 0
	v_addc_co_u32_e32 v5, vcc, 0, v3, vcc
	global_load_dwordx4 v[58:61], v[4:5], off
	v_add_co_u32_e32 v4, vcc, s4, v2
	s_mov_b32 s4, 0xc000
	s_nop 0
	v_addc_co_u32_e32 v5, vcc, 0, v3, vcc
	global_load_dwordx4 v[62:65], v[4:5], off
	v_add_co_u32_e32 v4, vcc, s4, v2
	s_mov_b32 s4, 0x10000
	s_nop 0
	v_addc_co_u32_e32 v5, vcc, 0, v3, vcc
	global_load_dwordx4 v[50:53], v[4:5], off
	v_add_co_u32_e32 v4, vcc, s4, v2
	s_mov_b32 s4, 0x14000
	s_nop 0
	v_addc_co_u32_e32 v5, vcc, 0, v3, vcc
	global_load_dwordx4 v[46:49], v[4:5], off
	v_add_co_u32_e32 v4, vcc, s4, v2
	s_mov_b32 s4, 0x18000
	s_nop 0
	v_addc_co_u32_e32 v5, vcc, 0, v3, vcc
	global_load_dwordx4 v[42:45], v[4:5], off
	v_add_co_u32_e32 v4, vcc, s4, v2
	s_mov_b32 s4, 0x1c000
	s_nop 0
	v_addc_co_u32_e32 v5, vcc, 0, v3, vcc
	global_load_dwordx4 v[38:41], v[4:5], off
	v_add_co_u32_e32 v4, vcc, s4, v2
	s_mov_b32 s4, 0x20000
	s_nop 0
	v_addc_co_u32_e32 v5, vcc, 0, v3, vcc
	global_load_dwordx4 v[34:37], v[4:5], off
	v_add_co_u32_e32 v4, vcc, s4, v2
	s_mov_b32 s4, 0x24000
	s_nop 0
	v_addc_co_u32_e32 v5, vcc, 0, v3, vcc
	global_load_dwordx4 v[30:33], v[4:5], off
	v_add_co_u32_e32 v4, vcc, s4, v2
	s_mov_b32 s4, 0x28000
	s_nop 0
	v_addc_co_u32_e32 v5, vcc, 0, v3, vcc
	global_load_dwordx4 v[26:29], v[4:5], off
	v_add_co_u32_e32 v4, vcc, s4, v2
	s_mov_b32 s4, 0x2c000
	s_nop 0
	v_addc_co_u32_e32 v5, vcc, 0, v3, vcc
	global_load_dwordx4 v[22:25], v[4:5], off
	v_add_co_u32_e32 v4, vcc, s4, v2
	s_mov_b32 s4, 0x30000
	s_nop 0
	v_addc_co_u32_e32 v5, vcc, 0, v3, vcc
	global_load_dwordx4 v[18:21], v[4:5], off
	v_add_co_u32_e32 v4, vcc, s4, v2
	ds_read_b128 v[104:107], v144
	s_nop 0
	v_addc_co_u32_e32 v5, vcc, 0, v3, vcc
	s_mov_b32 s4, 0x34000
	global_load_dwordx4 v[14:17], v[4:5], off
	v_add_co_u32_e32 v4, vcc, s4, v2
	s_mov_b32 s4, 0x38000
	s_nop 0
	v_addc_co_u32_e32 v5, vcc, 0, v3, vcc
	global_load_dwordx4 v[10:13], v[4:5], off
	v_add_co_u32_e32 v4, vcc, s4, v2
	s_mov_b32 s4, 0x3c000
	s_nop 0
	v_addc_co_u32_e32 v5, vcc, 0, v3, vcc
	s_waitcnt vmcnt(13) lgkmcnt(0)
	v_pk_fma_f32 v[104:105], v[54:55], s[70:71], v[104:105] op_sel_hi:[1,0,1]
	v_lshl_add_u64 v[54:55], s[78:79], 0, v[108:109]
	v_mov_b32_e32 v71, v1
	v_add_co_u32_e32 v2, vcc, s4, v2
	v_pk_fma_f32 v[106:107], v[56:57], s[70:71], v[106:107] op_sel_hi:[1,0,1]
	v_lshl_add_u64 v[56:57], v[54:55], 0, v[70:71]
	v_mov_b32_e32 v73, v1
	v_addc_co_u32_e32 v3, vcc, 0, v3, vcc
	v_lshl_add_u64 v[56:57], v[56:57], 0, v[72:73]
	global_load_dwordx4 v[6:9], v[4:5], off
	v_mov_b32_e32 v75, v1
	global_load_dwordx4 v[2:5], v[2:3], off
	v_mov_b32_e32 v77, v1
	global_store_dwordx4 v[56:57], v[104:107], off
	ds_read_b128 v[104:107], v145
	v_lshl_add_u64 v[56:57], v[54:55], 0, v[74:75]
	v_lshl_add_u64 v[56:57], v[56:57], 0, v[72:73]
	v_mov_b32_e32 v79, v1
	v_mov_b32_e32 v81, v1
	s_waitcnt vmcnt(15) lgkmcnt(0)
	v_pk_fma_f32 v[60:61], v[60:61], s[70:71], v[106:107] op_sel_hi:[1,0,1]
	v_pk_fma_f32 v[58:59], v[58:59], s[70:71], v[104:105] op_sel_hi:[1,0,1]
	global_store_dwordx4 v[56:57], v[58:61], off
	ds_read_b128 v[56:59], v146
	v_mov_b32_e32 v83, v1
	v_lshl_add_u64 v[60:61], v[54:55], 0, v[76:77]
	v_lshl_add_u64 v[60:61], v[60:61], 0, v[72:73]
	v_mov_b32_e32 v85, v1
	s_waitcnt vmcnt(15) lgkmcnt(0)
	v_pk_fma_f32 v[58:59], v[64:65], s[70:71], v[58:59] op_sel_hi:[1,0,1]
	v_pk_fma_f32 v[56:57], v[62:63], s[70:71], v[56:57] op_sel_hi:[1,0,1]
	global_store_dwordx4 v[60:61], v[56:59], off
	ds_read_b128 v[56:59], v147
	v_mov_b32_e32 v87, v1
	v_mov_b32_e32 v89, v1
	v_mov_b32_e32 v91, v1
	v_mov_b32_e32 v93, v1
	s_waitcnt vmcnt(15) lgkmcnt(0)
	v_pk_fma_f32 v[50:51], v[50:51], s[70:71], v[56:57] op_sel_hi:[1,0,1]
	v_lshl_add_u64 v[56:57], v[54:55], 0, v[78:79]
	v_pk_fma_f32 v[52:53], v[52:53], s[70:71], v[58:59] op_sel_hi:[1,0,1]
	v_lshl_add_u64 v[56:57], v[56:57], 0, v[72:73]
	global_store_dwordx4 v[56:57], v[50:53], off
	ds_read_b128 v[50:53], v148
	v_mov_b32_e32 v95, v1
	v_mov_b32_e32 v97, v1
	v_mov_b32_e32 v99, v1
	v_mov_b32_e32 v101, v1
	s_waitcnt vmcnt(15) lgkmcnt(0)
	v_pk_fma_f32 v[46:47], v[46:47], s[70:71], v[50:51] op_sel_hi:[1,0,1]
	v_lshl_add_u64 v[50:51], v[54:55], 0, v[80:81]
	v_pk_fma_f32 v[48:49], v[48:49], s[70:71], v[52:53] op_sel_hi:[1,0,1]
	v_lshl_add_u64 v[50:51], v[50:51], 0, v[72:73]
	global_store_dwordx4 v[50:51], v[46:49], off
	ds_read_b128 v[46:49], v149
	v_mov_b32_e32 v103, v1
	s_add_i32 s14, s14, 1
	s_mov_b64 s[10:11], 0
	s_waitcnt vmcnt(15) lgkmcnt(0)
	v_pk_fma_f32 v[42:43], v[42:43], s[70:71], v[46:47] op_sel_hi:[1,0,1]
	v_lshl_add_u64 v[46:47], v[54:55], 0, v[82:83]
	v_pk_fma_f32 v[44:45], v[44:45], s[70:71], v[48:49] op_sel_hi:[1,0,1]
	v_lshl_add_u64 v[46:47], v[46:47], 0, v[72:73]
	global_store_dwordx4 v[46:47], v[42:45], off
	ds_read_b128 v[42:45], v150
	s_waitcnt vmcnt(15) lgkmcnt(0)
	v_pk_fma_f32 v[38:39], v[38:39], s[70:71], v[42:43] op_sel_hi:[1,0,1]
	v_lshl_add_u64 v[42:43], v[54:55], 0, v[84:85]
	v_pk_fma_f32 v[40:41], v[40:41], s[70:71], v[44:45] op_sel_hi:[1,0,1]
	v_lshl_add_u64 v[42:43], v[42:43], 0, v[72:73]
	global_store_dwordx4 v[42:43], v[38:41], off
	ds_read_b128 v[38:41], v151
	s_waitcnt vmcnt(15) lgkmcnt(0)
	v_pk_fma_f32 v[34:35], v[34:35], s[70:71], v[38:39] op_sel_hi:[1,0,1]
	v_lshl_add_u64 v[38:39], v[54:55], 0, v[86:87]
	v_pk_fma_f32 v[36:37], v[36:37], s[70:71], v[40:41] op_sel_hi:[1,0,1]
	v_lshl_add_u64 v[38:39], v[38:39], 0, v[72:73]
	global_store_dwordx4 v[38:39], v[34:37], off
	ds_read_b128 v[34:37], v152
	s_waitcnt vmcnt(15) lgkmcnt(0)
	v_pk_fma_f32 v[30:31], v[30:31], s[70:71], v[34:35] op_sel_hi:[1,0,1]
	v_lshl_add_u64 v[34:35], v[54:55], 0, v[88:89]
	v_pk_fma_f32 v[32:33], v[32:33], s[70:71], v[36:37] op_sel_hi:[1,0,1]
	v_lshl_add_u64 v[34:35], v[34:35], 0, v[72:73]
	global_store_dwordx4 v[34:35], v[30:33], off
	ds_read_b128 v[30:33], v153
	s_waitcnt vmcnt(15) lgkmcnt(0)
	v_pk_fma_f32 v[26:27], v[26:27], s[70:71], v[30:31] op_sel_hi:[1,0,1]
	v_lshl_add_u64 v[30:31], v[54:55], 0, v[90:91]
	v_pk_fma_f32 v[28:29], v[28:29], s[70:71], v[32:33] op_sel_hi:[1,0,1]
	v_lshl_add_u64 v[30:31], v[30:31], 0, v[72:73]
	global_store_dwordx4 v[30:31], v[26:29], off
	ds_read_b128 v[26:29], v154
	s_waitcnt vmcnt(15) lgkmcnt(0)
	v_pk_fma_f32 v[22:23], v[22:23], s[70:71], v[26:27] op_sel_hi:[1,0,1]
	v_lshl_add_u64 v[26:27], v[54:55], 0, v[92:93]
	v_pk_fma_f32 v[24:25], v[24:25], s[70:71], v[28:29] op_sel_hi:[1,0,1]
	v_lshl_add_u64 v[26:27], v[26:27], 0, v[72:73]
	global_store_dwordx4 v[26:27], v[22:25], off
	ds_read_b128 v[22:25], v155
	s_waitcnt vmcnt(15) lgkmcnt(0)
	v_pk_fma_f32 v[18:19], v[18:19], s[70:71], v[22:23] op_sel_hi:[1,0,1]
	v_lshl_add_u64 v[22:23], v[54:55], 0, v[94:95]
	v_pk_fma_f32 v[20:21], v[20:21], s[70:71], v[24:25] op_sel_hi:[1,0,1]
	v_lshl_add_u64 v[22:23], v[22:23], 0, v[72:73]
	global_store_dwordx4 v[22:23], v[18:21], off
	ds_read_b128 v[18:21], v180
	s_waitcnt vmcnt(15) lgkmcnt(0)
	v_pk_fma_f32 v[14:15], v[14:15], s[70:71], v[18:19] op_sel_hi:[1,0,1]
	v_lshl_add_u64 v[18:19], v[54:55], 0, v[96:97]
	v_pk_fma_f32 v[16:17], v[16:17], s[70:71], v[20:21] op_sel_hi:[1,0,1]
	v_lshl_add_u64 v[18:19], v[18:19], 0, v[72:73]
	global_store_dwordx4 v[18:19], v[14:17], off
	ds_read_b128 v[14:17], v181
	s_waitcnt vmcnt(15) lgkmcnt(0)
	v_pk_fma_f32 v[10:11], v[10:11], s[70:71], v[14:15] op_sel_hi:[1,0,1]
	v_lshl_add_u64 v[14:15], v[54:55], 0, v[98:99]
	v_pk_fma_f32 v[12:13], v[12:13], s[70:71], v[16:17] op_sel_hi:[1,0,1]
	v_lshl_add_u64 v[14:15], v[14:15], 0, v[72:73]
	global_store_dwordx4 v[14:15], v[10:13], off
	ds_read_b128 v[10:13], v182
	s_waitcnt vmcnt(15) lgkmcnt(0)
	v_pk_fma_f32 v[6:7], v[6:7], s[70:71], v[10:11] op_sel_hi:[1,0,1]
	v_lshl_add_u64 v[10:11], v[54:55], 0, v[100:101]
	v_pk_fma_f32 v[8:9], v[8:9], s[70:71], v[12:13] op_sel_hi:[1,0,1]
	v_lshl_add_u64 v[10:11], v[10:11], 0, v[72:73]
	global_store_dwordx4 v[10:11], v[6:9], off
	ds_read_b128 v[6:9], v183
	s_waitcnt vmcnt(15) lgkmcnt(0)
	v_pk_fma_f32 v[2:3], v[2:3], s[70:71], v[6:7] op_sel_hi:[1,0,1]
	v_lshl_add_u64 v[6:7], v[54:55], 0, v[102:103]
	v_pk_fma_f32 v[4:5], v[4:5], s[70:71], v[8:9] op_sel_hi:[1,0,1]
	v_lshl_add_u64 v[6:7], v[6:7], 0, v[72:73]
	global_store_dwordx4 v[6:7], v[2:5], off
	s_cmp_eq_u32 s72, 0
	s_cbranch_scc0 .Lpo_done
	s_mov_b32 s72, 1
	s_mov_b32 s4, s26
	s_add_i32 s6, s27, 8
	s_mov_b32 s7, 0
	v_mov_b32_e32 v50, v128
	v_mov_b32_e32 v51, v129
	v_mov_b32_e32 v52, v130
	v_mov_b32_e32 v53, v131
	v_mov_b32_e32 v54, v132
	v_mov_b32_e32 v55, v133
	v_mov_b32_e32 v56, v134
	v_mov_b32_e32 v57, v135
	v_mov_b32_e32 v58, v136
	v_mov_b32_e32 v59, v137
	v_mov_b32_e32 v60, v138
	v_mov_b32_e32 v61, v139
	v_mov_b32_e32 v62, v140
	v_mov_b32_e32 v63, v141
	v_mov_b32_e32 v64, v142
	v_mov_b32_e32 v65, v143
	v_mov_b32_e32 v34, v184
	v_mov_b32_e32 v35, v185
	v_mov_b32_e32 v36, v186
	v_mov_b32_e32 v37, v187
	v_mov_b32_e32 v38, v188
	v_mov_b32_e32 v39, v189
	v_mov_b32_e32 v40, v190
	v_mov_b32_e32 v41, v191
	v_mov_b32_e32 v42, v192
	v_mov_b32_e32 v43, v193
	v_mov_b32_e32 v44, v194
	v_mov_b32_e32 v45, v195
	v_mov_b32_e32 v46, v196
	v_mov_b32_e32 v47, v197
	v_mov_b32_e32 v48, v198
	v_mov_b32_e32 v49, v199
	v_mov_b32_e32 v18, v200
	v_mov_b32_e32 v19, v201
	v_mov_b32_e32 v20, v202
	v_mov_b32_e32 v21, v203
	v_mov_b32_e32 v22, v204
	v_mov_b32_e32 v23, v205
	v_mov_b32_e32 v24, v206
	v_mov_b32_e32 v25, v207
	v_mov_b32_e32 v26, v208
	v_mov_b32_e32 v27, v209
	v_mov_b32_e32 v28, v210
	v_mov_b32_e32 v29, v211
	v_mov_b32_e32 v30, v212
	v_mov_b32_e32 v31, v213
	v_mov_b32_e32 v32, v214
	v_mov_b32_e32 v33, v215
	v_mov_b32_e32 v2, v216
	v_mov_b32_e32 v3, v217
	v_mov_b32_e32 v4, v218
	v_mov_b32_e32 v5, v219
	v_mov_b32_e32 v6, v220
	v_mov_b32_e32 v7, v221
	v_mov_b32_e32 v8, v222
	v_mov_b32_e32 v9, v223
	v_mov_b32_e32 v10, v224
	v_mov_b32_e32 v11, v225
	v_mov_b32_e32 v12, v226
	v_mov_b32_e32 v13, v227
	v_mov_b32_e32 v14, v228
	v_mov_b32_e32 v15, v229
	v_mov_b32_e32 v16, v230
	v_mov_b32_e32 v17, v231
	s_branch .LBB0_993
.Lpo_done:
.LBB0_994:
	s_and_b64 vcc, exec, s[10:11]
	s_cbranch_vccnz .LBB0_1007

.LBB0_1002:
	s_mov_b64 s[10:11], -1
	s_and_b64 vcc, exec, s[8:9]
	s_cbranch_vccz .LBB0_994
	s_ashr_i32 s7, s6, 31
	s_lshl_b64 s[8:9], s[6:7], 18
	s_add_u32 s16, s82, s8
	s_addc_u32 s17, s83, s9
	s_ashr_i32 s5, s4, 31
	s_lshl_b64 s[10:11], s[4:5], 18
	v_mov_b32_e32 v38, v156
	s_add_u32 s22, s12, s10
	s_addc_u32 s23, s13, s11
	v_readfirstlane_b32 s24, v38
	s_ashr_i32 s5, s24, 6
	v_bfe_u32 v0, v38, 3, 3
	v_lshl_or_b32 v2, s5, 5, v0
	v_min_i32_e32 v4, 0x7f, v2
	v_or_b32_e32 v10, 8, v2
	v_ashrrev_i32_e32 v5, 31, v4
	v_lshrrev_b32_e32 v11, 1, v10
	v_lshlrev_b64 v[4:5], 11, v[4:5]
	v_lshlrev_b32_e32 v0, 4, v38
	s_waitcnt vmcnt(0)
	v_and_b32_e32 v40, 48, v38
	v_ashrrev_i32_e32 v3, 31, v2
	v_xor_b32_e32 v11, v11, v38
	v_min_i32_e32 v12, 0x7f, v10
	v_or_b32_e32 v20, 16, v2
	v_or_b32_e32 v28, 24, v2
	v_lshl_add_u64 v[4:5], s[16:17], 0, v[4:5]
	v_and_b32_e32 v41, 0x70, v0
	v_bitop3_b32 v0, v0, v40, s19 bitop3:0x6c
	v_lshlrev_b64 v[6:7], 11, v[2:3]
	v_ashrrev_i32_e32 v13, 31, v12
	v_lshlrev_b32_e32 v11, 4, v11
	v_min_i32_e32 v22, 0x7f, v20
	v_min_i32_e32 v30, 0x7f, v28
	s_lshl_b32 s5, s5, 12
	v_lshl_add_u64 v[4:5], v[4:5], 0, v[0:1]
	v_lshl_add_u64 v[8:9], s[22:23], 0, v[6:7]
	v_lshlrev_b64 v[12:13], 11, v[12:13]
	v_and_b32_e32 v14, 0x70, v11
	v_ashrrev_i32_e32 v11, 31, v10
	v_ashrrev_i32_e32 v23, 31, v22
	v_ashrrev_i32_e32 v31, 31, v30
	s_add_i32 s15, s5, 0x4000
	s_mov_b32 m0, s5
	v_lshl_add_u64 v[8:9], v[8:9], 0, v[0:1]
	v_lshl_add_u64 v[12:13], s[16:17], 0, v[12:13]
	v_mov_b32_e32 v15, v1
	v_lshlrev_b64 v[16:17], 11, v[10:11]
	v_lshlrev_b64 v[22:23], 11, v[22:23]
	v_lshrrev_b32_e32 v29, 1, v28
	v_lshlrev_b64 v[30:31], 11, v[30:31]
	s_barrier
	global_load_lds_dwordx4 v[4:5], off
	s_mov_b32 m0, s15
	v_lshl_add_u64 v[12:13], v[12:13], 0, v[14:15]
	v_lshl_add_u64 v[18:19], s[22:23], 0, v[16:17]
	v_lshl_add_u64 v[22:23], s[16:17], 0, v[22:23]
	v_ashrrev_i32_e32 v21, 31, v20
	v_xor_b32_e32 v29, v29, v38
	v_lshl_add_u64 v[30:31], s[16:17], 0, v[30:31]
	global_load_lds_dwordx4 v[8:9], off
	s_or_b32 m0, s5, 0x400
	s_add_i32 s16, s5, 0x4400
	v_lshl_add_u64 v[18:19], v[18:19], 0, v[14:15]
	v_lshlrev_b64 v[24:25], 11, v[20:21]
	v_lshlrev_b32_e32 v29, 4, v29
	global_load_lds_dwordx4 v[12:13], off
	s_mov_b32 m0, s16
	v_lshl_add_u64 v[22:23], v[22:23], 0, v[0:1]
	v_lshl_add_u64 v[26:27], s[22:23], 0, v[24:25]
	v_and_b32_e32 v32, 0x70, v29
	v_ashrrev_i32_e32 v29, 31, v28
	global_load_lds_dwordx4 v[18:19], off
	s_or_b32 m0, s5, 0x800
	s_add_i32 s17, s5, 0x4800
	v_lshl_add_u64 v[26:27], v[26:27], 0, v[0:1]
	v_mov_b32_e32 v33, v1
	v_lshlrev_b64 v[34:35], 11, v[28:29]
	global_load_lds_dwordx4 v[22:23], off
	s_mov_b32 m0, s17
	v_lshl_add_u64 v[30:31], v[30:31], 0, v[32:33]
	v_lshl_add_u64 v[36:37], s[22:23], 0, v[34:35]
	global_load_lds_dwordx4 v[26:27], off
	s_or_b32 m0, s5, 0xc00
	s_add_i32 s22, s5, 0x4c00
	v_lshl_add_u64 v[36:37], v[36:37], 0, v[32:33]
	global_load_lds_dwordx4 v[30:31], off
	s_mov_b32 m0, s22
	s_lshr_b32 s23, s24, 1
	global_load_lds_dwordx4 v[36:37], off
	s_and_b32 s23, s23, 0x1ffffc0
	v_cmp_gt_i64_e32 vcc, s[30:31], v[2:3]
	s_add_u32 s10, s0, s10
	s_addc_u32 s11, s1, s11
	v_cndmask_b32_e32 v3, 0, v3, vcc
	v_cndmask_b32_e32 v2, v164, v2, vcc
	v_lshlrev_b64 v[2:3], 11, v[2:3]
	v_lshl_add_u64 v[104:105], s[8:9], 0, v[2:3]
	v_lshl_add_u64 v[2:3], s[10:11], 0, v[6:7]
	v_cmp_gt_i64_e32 vcc, s[30:31], v[10:11]
	v_lshl_add_u64 v[106:107], v[2:3], 0, v[0:1]
	v_and_b32_e32 v39, 31, v38
	v_cndmask_b32_e32 v3, 0, v11, vcc
	v_cndmask_b32_e32 v2, v164, v10, vcc
	v_lshlrev_b64 v[2:3], 11, v[2:3]
	v_lshl_add_u64 v[108:109], s[8:9], 0, v[2:3]
	v_lshl_add_u64 v[2:3], s[10:11], 0, v[16:17]
	v_cmp_gt_i64_e32 vcc, s[30:31], v[20:21]
	v_bfe_u32 v4, v38, 5, 1
	v_lshrrev_b32_e32 v5, 1, v38
	v_lshl_add_u64 v[110:111], v[2:3], 0, v[14:15]
	v_cndmask_b32_e32 v3, 0, v21, vcc
	v_cndmask_b32_e32 v2, v164, v20, vcc
	v_or_b32_e32 v9, s23, v39
	v_and_or_b32 v12, s24, 64, v39
	v_bitop3_b32 v5, v4, v5, 7 bitop3:0x78
	v_lshlrev_b64 v[2:3], 11, v[2:3]
	v_bfe_u32 v8, v38, 1, 3
	v_lshlrev_b32_e32 v9, 7, v9
	v_lshl_or_b32 v12, v12, 7, v163
	v_lshlrev_b32_e32 v5, 4, v5
	v_lshl_add_u64 v[112:113], s[8:9], 0, v[2:3]
	v_lshl_add_u64 v[2:3], s[10:11], 0, v[24:25]
	v_cmp_gt_i64_e32 vcc, s[30:31], v[28:29]
	v_or_b32_e32 v68, v9, v5
	v_or_b32_e32 v69, v12, v5
	v_bitop3_b32 v5, v4, v8, 2 bitop3:0x36
	v_lshl_add_u64 v[114:115], v[2:3], 0, v[0:1]
	v_cndmask_b32_e32 v3, 0, v29, vcc
	v_cndmask_b32_e32 v2, v164, v28, vcc
	v_lshlrev_b32_e32 v5, 4, v5
	v_lshlrev_b64 v[2:3], 11, v[2:3]
	s_waitcnt vmcnt(0)
	v_or_b32_e32 v70, v9, v5
	v_or_b32_e32 v71, v12, v5
	v_bitop3_b32 v5, v4, v8, 4 bitop3:0x36
	v_bitop3_b32 v4, v4, v8, 6 bitop3:0x36
	v_lshl_add_u64 v[116:117], s[8:9], 0, v[2:3]
	v_lshl_add_u64 v[2:3], s[10:11], 0, v[34:35]
	v_lshlrev_b32_e32 v5, 4, v5
	v_lshlrev_b32_e32 v4, 4, v4
	v_lshl_add_u64 v[118:119], v[2:3], 0, v[32:33]
	v_mov_b32_e32 v2, 0
	v_or_b32_e32 v72, v9, v5
	v_or_b32_e32 v73, v12, v5
	v_or_b32_e32 v74, v9, v4
	v_or_b32_e32 v75, v12, v4
	s_mov_b32 s23, 0
	v_bitop3_b32 v104, v104, v41, v40 bitop3:0xf6
	v_or_b32_e32 v108, v108, v14
	v_bitop3_b32 v112, v112, v41, v40 bitop3:0xf6
	v_or_b32_e32 v116, v116, v32
	v_mov_b32_e32 v3, v2
	v_mov_b32_e32 v4, v2
	v_mov_b32_e32 v5, v2
	v_mov_b32_e32 v6, v2
	v_mov_b32_e32 v7, v2
	v_mov_b32_e32 v8, v2
	v_mov_b32_e32 v9, v2
	v_mov_b32_e32 v10, v2
	v_mov_b32_e32 v11, v2
	v_mov_b32_e32 v12, v2
	v_mov_b32_e32 v13, v2
	v_mov_b32_e32 v14, v2
	v_mov_b32_e32 v15, v2
	v_mov_b32_e32 v16, v2
	v_mov_b32_e32 v17, v2
	v_mov_b32_e32 v18, v2
	v_mov_b32_e32 v19, v2
	v_mov_b32_e32 v20, v2
	v_mov_b32_e32 v21, v2
	v_mov_b32_e32 v22, v2
	v_mov_b32_e32 v23, v2
	v_mov_b32_e32 v24, v2
	v_mov_b32_e32 v25, v2
	v_mov_b32_e32 v26, v2
	v_mov_b32_e32 v27, v2
	v_mov_b32_e32 v28, v2
	v_mov_b32_e32 v29, v2
	v_mov_b32_e32 v30, v2
	v_mov_b32_e32 v31, v2
	v_mov_b32_e32 v32, v2
	v_mov_b32_e32 v33, v2
	v_mov_b32_e32 v34, v2
	v_mov_b32_e32 v35, v2
	v_mov_b32_e32 v36, v2
	v_mov_b32_e32 v37, v2
	v_mov_b32_e32 v38, v2
	v_mov_b32_e32 v39, v2
	v_mov_b32_e32 v40, v2
	v_mov_b32_e32 v41, v2
	v_mov_b32_e32 v42, v2
	v_mov_b32_e32 v43, v2
	v_mov_b32_e32 v44, v2
	v_mov_b32_e32 v45, v2
	v_mov_b32_e32 v46, v2
	v_mov_b32_e32 v47, v2
	v_mov_b32_e32 v48, v2
	v_mov_b32_e32 v49, v2
	v_mov_b32_e32 v50, v2
	v_mov_b32_e32 v51, v2
	v_mov_b32_e32 v52, v2
	v_mov_b32_e32 v53, v2
	v_mov_b32_e32 v54, v2
	v_mov_b32_e32 v55, v2
	v_mov_b32_e32 v56, v2
	v_mov_b32_e32 v57, v2
	v_mov_b32_e32 v58, v2
	v_mov_b32_e32 v59, v2
	v_mov_b32_e32 v60, v2
	v_mov_b32_e32 v61, v2
	v_mov_b32_e32 v62, v2
	v_mov_b32_e32 v63, v2
	v_mov_b32_e32 v64, v2
	v_mov_b32_e32 v65, v2
	s_waitcnt vmcnt(0) lgkmcnt(0)
	s_barrier
	s_mov_b32 s26, s4
	s_mov_b32 s27, s6
	s_mov_b32 s72, 0
	v_lshl_add_u64 v[104:105], s[80:81], 0, v[104:105]
	v_lshl_add_u64 v[104:105], v[104:105], 0, s[88:89]
	v_lshl_add_u64 v[106:107], s[80:81], 0, v[106:107]
	v_lshl_add_u64 v[106:107], v[106:107], 0, s[90:91]
	v_lshl_add_u64 v[108:109], s[80:81], 0, v[108:109]
	v_lshl_add_u64 v[108:109], v[108:109], 0, s[88:89]
	v_lshl_add_u64 v[110:111], s[80:81], 0, v[110:111]
	v_lshl_add_u64 v[110:111], v[110:111], 0, s[90:91]
	v_lshl_add_u64 v[112:113], s[80:81], 0, v[112:113]
	v_lshl_add_u64 v[112:113], v[112:113], 0, s[88:89]
	v_lshl_add_u64 v[114:115], s[80:81], 0, v[114:115]
	v_lshl_add_u64 v[114:115], v[114:115], 0, s[90:91]
	v_lshl_add_u64 v[116:117], s[80:81], 0, v[116:117]
	v_lshl_add_u64 v[116:117], v[116:117], 0, s[88:89]
	v_lshl_add_u64 v[118:119], s[80:81], 0, v[118:119]
	v_lshl_add_u64 v[118:119], v[118:119], 0, s[90:91]
	s_mov_b64 s[8:9], 0x200000
	s_mov_b64 s[10:11], 0x1fff80
	s_add_i32 m0, s5, 0x8000
	v_lshl_add_u64 v[66:67], v[104:105], 0, s[10:11]
	s_nop 0
	global_load_lds_dwordx4 v[66:67], off
	s_add_i32 m0, s5, 0x8400
	v_lshl_add_u64 v[66:67], v[108:109], 0, s[10:11]
	s_nop 0
	global_load_lds_dwordx4 v[66:67], off
	s_add_i32 m0, s5, 0x8800
	v_lshl_add_u64 v[66:67], v[112:113], 0, s[10:11]
	s_nop 0
	global_load_lds_dwordx4 v[66:67], off
	s_add_i32 m0, s5, 0x8c00
	v_lshl_add_u64 v[66:67], v[116:117], 0, s[10:11]
	s_nop 0
	global_load_lds_dwordx4 v[66:67], off
	s_add_i32 m0, s5, 0xc000
	s_nop 0
	global_load_lds_dwordx4 v[106:107], off
	v_lshl_add_u64 v[106:107], v[106:107], 0, s[34:35]
	s_add_i32 m0, s5, 0xc400
	s_nop 0
	global_load_lds_dwordx4 v[110:111], off
	v_lshl_add_u64 v[110:111], v[110:111], 0, s[34:35]
	s_add_i32 m0, s5, 0xc800
	s_nop 0
	global_load_lds_dwordx4 v[114:115], off
	v_lshl_add_u64 v[114:115], v[114:115], 0, s[34:35]
	s_add_i32 m0, s5, 0xcc00
	s_nop 0
	global_load_lds_dwordx4 v[118:119], off
	v_lshl_add_u64 v[118:119], v[118:119], 0, s[34:35]
	v_mov_b32_e32 v128, 0
	v_mov_b32_e32 v129, 0
	v_mov_b32_e32 v130, 0
	v_mov_b32_e32 v131, 0
	v_mov_b32_e32 v132, 0
	v_mov_b32_e32 v133, 0
	v_mov_b32_e32 v134, 0
	v_mov_b32_e32 v135, 0
	v_mov_b32_e32 v136, 0
	v_mov_b32_e32 v137, 0
	v_mov_b32_e32 v138, 0
	v_mov_b32_e32 v139, 0
	v_mov_b32_e32 v140, 0
	v_mov_b32_e32 v141, 0
	v_mov_b32_e32 v142, 0
	v_mov_b32_e32 v143, 0
	v_mov_b32_e32 v184, 0
	v_mov_b32_e32 v185, 0
	v_mov_b32_e32 v186, 0
	v_mov_b32_e32 v187, 0
	v_mov_b32_e32 v188, 0
	v_mov_b32_e32 v189, 0
	v_mov_b32_e32 v190, 0
	v_mov_b32_e32 v191, 0
	v_mov_b32_e32 v192, 0
	v_mov_b32_e32 v193, 0
	v_mov_b32_e32 v194, 0
	v_mov_b32_e32 v195, 0
	v_mov_b32_e32 v196, 0
	v_mov_b32_e32 v197, 0
	v_mov_b32_e32 v198, 0
	v_mov_b32_e32 v199, 0
	v_mov_b32_e32 v200, 0
	v_mov_b32_e32 v201, 0
	v_mov_b32_e32 v202, 0
	v_mov_b32_e32 v203, 0
	v_mov_b32_e32 v204, 0
	v_mov_b32_e32 v205, 0
	v_mov_b32_e32 v206, 0
	v_mov_b32_e32 v207, 0
	v_mov_b32_e32 v208, 0
	v_mov_b32_e32 v209, 0
	v_mov_b32_e32 v210, 0
	v_mov_b32_e32 v211, 0
	v_mov_b32_e32 v212, 0
	v_mov_b32_e32 v213, 0
	v_mov_b32_e32 v214, 0
	v_mov_b32_e32 v215, 0
	v_mov_b32_e32 v216, 0
	v_mov_b32_e32 v217, 0
	v_mov_b32_e32 v218, 0
	v_mov_b32_e32 v219, 0
	v_mov_b32_e32 v220, 0
	v_mov_b32_e32 v221, 0
	v_mov_b32_e32 v222, 0
	v_mov_b32_e32 v223, 0
	v_mov_b32_e32 v224, 0
	v_mov_b32_e32 v225, 0
	v_mov_b32_e32 v226, 0
	v_mov_b32_e32 v227, 0
	v_mov_b32_e32 v228, 0
	v_mov_b32_e32 v229, 0
	v_mov_b32_e32 v230, 0
	v_mov_b32_e32 v231, 0
	s_mov_b32 s23, 0
.Lg1o_loop:
	ds_read_b128 v[76:79], v68 offset:0
	ds_read_b128 v[80:83], v68 offset:4096
	ds_read_b128 v[148:151], v69 offset:0
	ds_read_b128 v[152:155], v69 offset:4096
	ds_read_b128 v[84:87], v70 offset:0
	ds_read_b128 v[88:91], v70 offset:4096
	ds_read_b128 v[180:183], v71 offset:0
	ds_read_b128 v[236:239], v71 offset:4096
	ds_read_b128 v[92:95], v72 offset:0
	ds_read_b128 v[96:99], v72 offset:4096
	ds_read_b128 v[240:243], v73 offset:0
	ds_read_b128 v[244:247], v73 offset:4096
	ds_read_b128 v[100:103], v74 offset:0
	ds_read_b128 v[144:147], v74 offset:4096
	ds_read_b128 v[248:251], v75 offset:0
	ds_read_b128 v[252:255], v75 offset:4096
	s_waitcnt lgkmcnt(0)
	s_barrier
	s_mov_b32 m0, s5
	v_mfma_f32_32x32x16_bf16 v[50:65], v[76:79], v[148:151], v[50:65]
	global_load_lds_dwordx4 v[104:105], off
	v_mfma_f32_32x32x16_bf16 v[34:49], v[76:79], v[152:155], v[34:49]
	s_add_i32 m0, s5, 0x400
	v_mfma_f32_32x32x16_bf16 v[18:33], v[80:83], v[148:151], v[18:33]
	global_load_lds_dwordx4 v[108:109], off
	v_mfma_f32_32x32x16_bf16 v[2:17], v[80:83], v[152:155], v[2:17]
	s_add_i32 m0, s5, 0x800
	v_mfma_f32_32x32x16_bf16 v[50:65], v[84:87], v[180:183], v[50:65]
	global_load_lds_dwordx4 v[112:113], off
	v_mfma_f32_32x32x16_bf16 v[34:49], v[84:87], v[236:239], v[34:49]
	s_add_i32 m0, s5, 0xc00
	v_mfma_f32_32x32x16_bf16 v[18:33], v[88:91], v[180:183], v[18:33]
	global_load_lds_dwordx4 v[116:117], off
	v_mfma_f32_32x32x16_bf16 v[2:17], v[88:91], v[236:239], v[2:17]
	s_mov_b32 m0, s15
	v_mfma_f32_32x32x16_bf16 v[50:65], v[92:95], v[240:243], v[50:65]
	global_load_lds_dwordx4 v[106:107], off
	v_lshl_add_u64 v[106:107], v[106:107], 0, s[34:35]
	v_mfma_f32_32x32x16_bf16 v[34:49], v[92:95], v[244:247], v[34:49]
	s_mov_b32 m0, s16
	v_mfma_f32_32x32x16_bf16 v[18:33], v[96:99], v[240:243], v[18:33]
	global_load_lds_dwordx4 v[110:111], off
	v_lshl_add_u64 v[110:111], v[110:111], 0, s[34:35]
	v_mfma_f32_32x32x16_bf16 v[2:17], v[96:99], v[244:247], v[2:17]
	v_mfma_f32_32x32x16_bf16 v[50:65], v[100:103], v[248:251], v[50:65]
	v_mfma_f32_32x32x16_bf16 v[34:49], v[100:103], v[252:255], v[34:49]
	v_mfma_f32_32x32x16_bf16 v[18:33], v[144:147], v[248:251], v[18:33]
	v_mfma_f32_32x32x16_bf16 v[2:17], v[144:147], v[252:255], v[2:17]
	s_waitcnt vmcnt(6)
	s_barrier
	ds_read_b128 v[76:79], v68 offset:32768
	ds_read_b128 v[80:83], v68 offset:36864
	ds_read_b128 v[84:87], v70 offset:32768
	ds_read_b128 v[88:91], v70 offset:36864
	ds_read_b128 v[92:95], v72 offset:32768
	ds_read_b128 v[96:99], v72 offset:36864
	ds_read_b128 v[100:103], v74 offset:32768
	ds_read_b128 v[144:147], v74 offset:36864
	s_waitcnt lgkmcnt(0)
	s_barrier
	s_add_i32 m0, s5, 0x8000
	v_lshl_add_u64 v[66:67], v[104:105], 0, s[8:9]
	v_mfma_f32_32x32x16_bf16 v[128:143], v[76:79], v[148:151], v[128:143]
	global_load_lds_dwordx4 v[66:67], off
	v_lshl_add_u64 v[104:105], v[104:105], 0, s[34:35]
	v_mfma_f32_32x32x16_bf16 v[184:199], v[76:79], v[152:155], v[184:199]
	s_add_i32 m0, s5, 0x8400
	v_lshl_add_u64 v[66:67], v[108:109], 0, s[8:9]
	v_mfma_f32_32x32x16_bf16 v[200:215], v[80:83], v[148:151], v[200:215]
	global_load_lds_dwordx4 v[66:67], off
	v_lshl_add_u64 v[108:109], v[108:109], 0, s[34:35]
	v_mfma_f32_32x32x16_bf16 v[216:231], v[80:83], v[152:155], v[216:231]
	s_add_i32 m0, s5, 0x8800
	v_lshl_add_u64 v[66:67], v[112:113], 0, s[8:9]
	v_mfma_f32_32x32x16_bf16 v[128:143], v[84:87], v[180:183], v[128:143]
	global_load_lds_dwordx4 v[66:67], off
	v_lshl_add_u64 v[112:113], v[112:113], 0, s[34:35]
	v_mfma_f32_32x32x16_bf16 v[184:199], v[84:87], v[236:239], v[184:199]
	s_add_i32 m0, s5, 0x8c00
	v_lshl_add_u64 v[66:67], v[116:117], 0, s[8:9]
	v_mfma_f32_32x32x16_bf16 v[200:215], v[88:91], v[180:183], v[200:215]
	global_load_lds_dwordx4 v[66:67], off
	v_lshl_add_u64 v[116:117], v[116:117], 0, s[34:35]
	v_mfma_f32_32x32x16_bf16 v[216:231], v[88:91], v[236:239], v[216:231]
	s_mov_b32 m0, s17
	v_mfma_f32_32x32x16_bf16 v[128:143], v[92:95], v[240:243], v[128:143]
	global_load_lds_dwordx4 v[114:115], off
	v_lshl_add_u64 v[114:115], v[114:115], 0, s[34:35]
	v_mfma_f32_32x32x16_bf16 v[184:199], v[92:95], v[244:247], v[184:199]
	s_mov_b32 m0, s22
	v_mfma_f32_32x32x16_bf16 v[200:215], v[96:99], v[240:243], v[200:215]
	global_load_lds_dwordx4 v[118:119], off
	v_lshl_add_u64 v[118:119], v[118:119], 0, s[34:35]
	v_mfma_f32_32x32x16_bf16 v[216:231], v[96:99], v[244:247], v[216:231]
	v_mfma_f32_32x32x16_bf16 v[128:143], v[100:103], v[248:251], v[128:143]
	v_mfma_f32_32x32x16_bf16 v[184:199], v[100:103], v[252:255], v[184:199]
	v_mfma_f32_32x32x16_bf16 v[200:215], v[144:147], v[248:251], v[200:215]
	v_mfma_f32_32x32x16_bf16 v[216:231], v[144:147], v[252:255], v[216:231]
	s_waitcnt vmcnt(6)
	s_barrier
	ds_read_b128 v[76:79], v68 offset:0
	ds_read_b128 v[80:83], v68 offset:4096
	ds_read_b128 v[148:151], v69 offset:32768
	ds_read_b128 v[152:155], v69 offset:36864
	ds_read_b128 v[84:87], v70 offset:0
	ds_read_b128 v[88:91], v70 offset:4096
	ds_read_b128 v[180:183], v71 offset:32768
	ds_read_b128 v[236:239], v71 offset:36864
	ds_read_b128 v[92:95], v72 offset:0
	ds_read_b128 v[96:99], v72 offset:4096
	ds_read_b128 v[240:243], v73 offset:32768
	ds_read_b128 v[244:247], v73 offset:36864
	ds_read_b128 v[100:103], v74 offset:0
	ds_read_b128 v[144:147], v74 offset:4096
	ds_read_b128 v[248:251], v75 offset:32768
	ds_read_b128 v[252:255], v75 offset:36864
	s_waitcnt lgkmcnt(0)
	s_barrier
	s_mov_b32 m0, s5
	v_mfma_f32_32x32x16_bf16 v[50:65], v[76:79], v[148:151], v[50:65]
	global_load_lds_dwordx4 v[104:105], off
	v_mfma_f32_32x32x16_bf16 v[34:49], v[76:79], v[152:155], v[34:49]
	s_add_i32 m0, s5, 0x400
	v_mfma_f32_32x32x16_bf16 v[18:33], v[80:83], v[148:151], v[18:33]
	global_load_lds_dwordx4 v[108:109], off
	v_mfma_f32_32x32x16_bf16 v[2:17], v[80:83], v[152:155], v[2:17]
	s_add_i32 m0, s5, 0x800
	v_mfma_f32_32x32x16_bf16 v[50:65], v[84:87], v[180:183], v[50:65]
	global_load_lds_dwordx4 v[112:113], off
	v_mfma_f32_32x32x16_bf16 v[34:49], v[84:87], v[236:239], v[34:49]
	s_add_i32 m0, s5, 0xc00
	v_mfma_f32_32x32x16_bf16 v[18:33], v[88:91], v[180:183], v[18:33]
	global_load_lds_dwordx4 v[116:117], off
	v_mfma_f32_32x32x16_bf16 v[2:17], v[88:91], v[236:239], v[2:17]
	s_add_i32 m0, s5, 0xc000
	v_mfma_f32_32x32x16_bf16 v[50:65], v[92:95], v[240:243], v[50:65]
	global_load_lds_dwordx4 v[106:107], off
	v_lshl_add_u64 v[106:107], v[106:107], 0, s[34:35]
	v_mfma_f32_32x32x16_bf16 v[34:49], v[92:95], v[244:247], v[34:49]
	s_add_i32 m0, s5, 0xc400
	v_mfma_f32_32x32x16_bf16 v[18:33], v[96:99], v[240:243], v[18:33]
	global_load_lds_dwordx4 v[110:111], off
	v_lshl_add_u64 v[110:111], v[110:111], 0, s[34:35]
	v_mfma_f32_32x32x16_bf16 v[2:17], v[96:99], v[244:247], v[2:17]
	v_mfma_f32_32x32x16_bf16 v[50:65], v[100:103], v[248:251], v[50:65]
	v_mfma_f32_32x32x16_bf16 v[34:49], v[100:103], v[252:255], v[34:49]
	v_mfma_f32_32x32x16_bf16 v[18:33], v[144:147], v[248:251], v[18:33]
	v_mfma_f32_32x32x16_bf16 v[2:17], v[144:147], v[252:255], v[2:17]
	s_waitcnt vmcnt(6)
	s_barrier
	ds_read_b128 v[76:79], v68 offset:32768
	ds_read_b128 v[80:83], v68 offset:36864
	ds_read_b128 v[84:87], v70 offset:32768
	ds_read_b128 v[88:91], v70 offset:36864
	ds_read_b128 v[92:95], v72 offset:32768
	ds_read_b128 v[96:99], v72 offset:36864
	ds_read_b128 v[100:103], v74 offset:32768
	ds_read_b128 v[144:147], v74 offset:36864
	s_waitcnt lgkmcnt(0)
	s_barrier
	s_add_i32 m0, s5, 0x8000
	v_lshl_add_u64 v[66:67], v[104:105], 0, s[8:9]
	v_mfma_f32_32x32x16_bf16 v[128:143], v[76:79], v[148:151], v[128:143]
	global_load_lds_dwordx4 v[66:67], off
	v_lshl_add_u64 v[104:105], v[104:105], 0, s[34:35]
	v_mfma_f32_32x32x16_bf16 v[184:199], v[76:79], v[152:155], v[184:199]
	s_add_i32 m0, s5, 0x8400
	v_lshl_add_u64 v[66:67], v[108:109], 0, s[8:9]
	v_mfma_f32_32x32x16_bf16 v[200:215], v[80:83], v[148:151], v[200:215]
	global_load_lds_dwordx4 v[66:67], off
	v_lshl_add_u64 v[108:109], v[108:109], 0, s[34:35]
	v_mfma_f32_32x32x16_bf16 v[216:231], v[80:83], v[152:155], v[216:231]
	s_add_i32 m0, s5, 0x8800
	v_lshl_add_u64 v[66:67], v[112:113], 0, s[8:9]
	v_mfma_f32_32x32x16_bf16 v[128:143], v[84:87], v[180:183], v[128:143]
	global_load_lds_dwordx4 v[66:67], off
	v_lshl_add_u64 v[112:113], v[112:113], 0, s[34:35]
	v_mfma_f32_32x32x16_bf16 v[184:199], v[84:87], v[236:239], v[184:199]
	s_add_i32 m0, s5, 0x8c00
	v_lshl_add_u64 v[66:67], v[116:117], 0, s[8:9]
	v_mfma_f32_32x32x16_bf16 v[200:215], v[88:91], v[180:183], v[200:215]
	global_load_lds_dwordx4 v[66:67], off
	v_lshl_add_u64 v[116:117], v[116:117], 0, s[34:35]
	v_mfma_f32_32x32x16_bf16 v[216:231], v[88:91], v[236:239], v[216:231]
	s_add_i32 m0, s5, 0xc800
	v_mfma_f32_32x32x16_bf16 v[128:143], v[92:95], v[240:243], v[128:143]
	global_load_lds_dwordx4 v[114:115], off
	v_lshl_add_u64 v[114:115], v[114:115], 0, s[34:35]
	v_mfma_f32_32x32x16_bf16 v[184:199], v[92:95], v[244:247], v[184:199]
	s_add_i32 m0, s5, 0xcc00
	v_mfma_f32_32x32x16_bf16 v[200:215], v[96:99], v[240:243], v[200:215]
	global_load_lds_dwordx4 v[118:119], off
	v_lshl_add_u64 v[118:119], v[118:119], 0, s[34:35]
	v_mfma_f32_32x32x16_bf16 v[216:231], v[96:99], v[244:247], v[216:231]
	v_mfma_f32_32x32x16_bf16 v[128:143], v[100:103], v[248:251], v[128:143]
	v_mfma_f32_32x32x16_bf16 v[184:199], v[100:103], v[252:255], v[184:199]
	v_mfma_f32_32x32x16_bf16 v[200:215], v[144:147], v[248:251], v[200:215]
	v_mfma_f32_32x32x16_bf16 v[216:231], v[144:147], v[252:255], v[216:231]
	s_waitcnt vmcnt(6)
	s_barrier
	s_add_i32 s23, s23, 2
	s_cmp_lt_u32 s23, 14
	s_cbranch_scc1 .Lg1o_loop
	ds_read_b128 v[76:79], v68 offset:0
	ds_read_b128 v[80:83], v68 offset:4096
	ds_read_b128 v[148:151], v69 offset:0
	ds_read_b128 v[152:155], v69 offset:4096
	ds_read_b128 v[84:87], v70 offset:0
	ds_read_b128 v[88:91], v70 offset:4096
	ds_read_b128 v[180:183], v71 offset:0
	ds_read_b128 v[236:239], v71 offset:4096
	ds_read_b128 v[92:95], v72 offset:0
	ds_read_b128 v[96:99], v72 offset:4096
	ds_read_b128 v[240:243], v73 offset:0
	ds_read_b128 v[244:247], v73 offset:4096
	ds_read_b128 v[100:103], v74 offset:0
	ds_read_b128 v[144:147], v74 offset:4096
	ds_read_b128 v[248:251], v75 offset:0
	ds_read_b128 v[252:255], v75 offset:4096
	s_waitcnt lgkmcnt(0)
	s_barrier
	s_mov_b32 m0, s5
	v_mfma_f32_32x32x16_bf16 v[50:65], v[76:79], v[148:151], v[50:65]
	global_load_lds_dwordx4 v[104:105], off
	v_mfma_f32_32x32x16_bf16 v[34:49], v[76:79], v[152:155], v[34:49]
	s_add_i32 m0, s5, 0x400
	v_mfma_f32_32x32x16_bf16 v[18:33], v[80:83], v[148:151], v[18:33]
	global_load_lds_dwordx4 v[108:109], off
	v_mfma_f32_32x32x16_bf16 v[2:17], v[80:83], v[152:155], v[2:17]
	s_add_i32 m0, s5, 0x800
	v_mfma_f32_32x32x16_bf16 v[50:65], v[84:87], v[180:183], v[50:65]
	global_load_lds_dwordx4 v[112:113], off
	v_mfma_f32_32x32x16_bf16 v[34:49], v[84:87], v[236:239], v[34:49]
	s_add_i32 m0, s5, 0xc00
	v_mfma_f32_32x32x16_bf16 v[18:33], v[88:91], v[180:183], v[18:33]
	global_load_lds_dwordx4 v[116:117], off
	v_mfma_f32_32x32x16_bf16 v[2:17], v[88:91], v[236:239], v[2:17]
	v_mfma_f32_32x32x16_bf16 v[50:65], v[92:95], v[240:243], v[50:65]
	v_mfma_f32_32x32x16_bf16 v[34:49], v[92:95], v[244:247], v[34:49]
	v_mfma_f32_32x32x16_bf16 v[18:33], v[96:99], v[240:243], v[18:33]
	v_mfma_f32_32x32x16_bf16 v[2:17], v[96:99], v[244:247], v[2:17]
	v_mfma_f32_32x32x16_bf16 v[50:65], v[100:103], v[248:251], v[50:65]
	v_mfma_f32_32x32x16_bf16 v[34:49], v[100:103], v[252:255], v[34:49]
	v_mfma_f32_32x32x16_bf16 v[18:33], v[144:147], v[248:251], v[18:33]
	v_mfma_f32_32x32x16_bf16 v[2:17], v[144:147], v[252:255], v[2:17]
	s_waitcnt vmcnt(4)
	s_barrier
	ds_read_b128 v[76:79], v68 offset:32768
	ds_read_b128 v[80:83], v68 offset:36864
	ds_read_b128 v[84:87], v70 offset:32768
	ds_read_b128 v[88:91], v70 offset:36864
	ds_read_b128 v[92:95], v72 offset:32768
	ds_read_b128 v[96:99], v72 offset:36864
	ds_read_b128 v[100:103], v74 offset:32768
	ds_read_b128 v[144:147], v74 offset:36864
	s_waitcnt lgkmcnt(0)
	s_barrier
	s_add_i32 m0, s5, 0x8000
	v_lshl_add_u64 v[66:67], v[104:105], 0, s[8:9]
	v_mfma_f32_32x32x16_bf16 v[128:143], v[76:79], v[148:151], v[128:143]
	global_load_lds_dwordx4 v[66:67], off
	v_lshl_add_u64 v[104:105], v[104:105], 0, s[34:35]
	v_mfma_f32_32x32x16_bf16 v[184:199], v[76:79], v[152:155], v[184:199]
	s_add_i32 m0, s5, 0x8400
	v_lshl_add_u64 v[66:67], v[108:109], 0, s[8:9]
	v_mfma_f32_32x32x16_bf16 v[200:215], v[80:83], v[148:151], v[200:215]
	global_load_lds_dwordx4 v[66:67], off
	v_lshl_add_u64 v[108:109], v[108:109], 0, s[34:35]
	v_mfma_f32_32x32x16_bf16 v[216:231], v[80:83], v[152:155], v[216:231]
	s_add_i32 m0, s5, 0x8800
	v_lshl_add_u64 v[66:67], v[112:113], 0, s[8:9]
	v_mfma_f32_32x32x16_bf16 v[128:143], v[84:87], v[180:183], v[128:143]
	global_load_lds_dwordx4 v[66:67], off
	v_lshl_add_u64 v[112:113], v[112:113], 0, s[34:35]
	v_mfma_f32_32x32x16_bf16 v[184:199], v[84:87], v[236:239], v[184:199]
	s_add_i32 m0, s5, 0x8c00
	v_lshl_add_u64 v[66:67], v[116:117], 0, s[8:9]
	v_mfma_f32_32x32x16_bf16 v[200:215], v[88:91], v[180:183], v[200:215]
	global_load_lds_dwordx4 v[66:67], off
	v_lshl_add_u64 v[116:117], v[116:117], 0, s[34:35]
	v_mfma_f32_32x32x16_bf16 v[216:231], v[88:91], v[236:239], v[216:231]
	v_mfma_f32_32x32x16_bf16 v[128:143], v[92:95], v[240:243], v[128:143]
	v_mfma_f32_32x32x16_bf16 v[184:199], v[92:95], v[244:247], v[184:199]
	v_mfma_f32_32x32x16_bf16 v[200:215], v[96:99], v[240:243], v[200:215]
	v_mfma_f32_32x32x16_bf16 v[216:231], v[96:99], v[244:247], v[216:231]
	v_mfma_f32_32x32x16_bf16 v[128:143], v[100:103], v[248:251], v[128:143]
	v_mfma_f32_32x32x16_bf16 v[184:199], v[100:103], v[252:255], v[184:199]
	v_mfma_f32_32x32x16_bf16 v[200:215], v[144:147], v[248:251], v[200:215]
	v_mfma_f32_32x32x16_bf16 v[216:231], v[144:147], v[252:255], v[216:231]
	s_waitcnt vmcnt(4)
	s_barrier
	ds_read_b128 v[76:79], v68 offset:0
	ds_read_b128 v[80:83], v68 offset:4096
	ds_read_b128 v[148:151], v69 offset:32768
	ds_read_b128 v[152:155], v69 offset:36864
	ds_read_b128 v[84:87], v70 offset:0
	ds_read_b128 v[88:91], v70 offset:4096
	ds_read_b128 v[180:183], v71 offset:32768
	ds_read_b128 v[236:239], v71 offset:36864
	ds_read_b128 v[92:95], v72 offset:0
	ds_read_b128 v[96:99], v72 offset:4096
	ds_read_b128 v[240:243], v73 offset:32768
	ds_read_b128 v[244:247], v73 offset:36864
	ds_read_b128 v[100:103], v74 offset:0
	ds_read_b128 v[144:147], v74 offset:4096
	ds_read_b128 v[248:251], v75 offset:32768
	ds_read_b128 v[252:255], v75 offset:36864
	s_waitcnt lgkmcnt(0)
	s_barrier
	v_mfma_f32_32x32x16_bf16 v[50:65], v[76:79], v[148:151], v[50:65]
	v_mfma_f32_32x32x16_bf16 v[34:49], v[76:79], v[152:155], v[34:49]
	v_mfma_f32_32x32x16_bf16 v[18:33], v[80:83], v[148:151], v[18:33]
	v_mfma_f32_32x32x16_bf16 v[2:17], v[80:83], v[152:155], v[2:17]
	v_mfma_f32_32x32x16_bf16 v[50:65], v[84:87], v[180:183], v[50:65]
	v_mfma_f32_32x32x16_bf16 v[34:49], v[84:87], v[236:239], v[34:49]
	v_mfma_f32_32x32x16_bf16 v[18:33], v[88:91], v[180:183], v[18:33]
	v_mfma_f32_32x32x16_bf16 v[2:17], v[88:91], v[236:239], v[2:17]
	v_mfma_f32_32x32x16_bf16 v[50:65], v[92:95], v[240:243], v[50:65]
	v_mfma_f32_32x32x16_bf16 v[34:49], v[92:95], v[244:247], v[34:49]
	v_mfma_f32_32x32x16_bf16 v[18:33], v[96:99], v[240:243], v[18:33]
	v_mfma_f32_32x32x16_bf16 v[2:17], v[96:99], v[244:247], v[2:17]
	v_mfma_f32_32x32x16_bf16 v[50:65], v[100:103], v[248:251], v[50:65]
	v_mfma_f32_32x32x16_bf16 v[34:49], v[100:103], v[252:255], v[34:49]
	v_mfma_f32_32x32x16_bf16 v[18:33], v[144:147], v[248:251], v[18:33]
	v_mfma_f32_32x32x16_bf16 v[2:17], v[144:147], v[252:255], v[2:17]
	s_waitcnt vmcnt(0)
	s_barrier
	ds_read_b128 v[76:79], v68 offset:32768
	ds_read_b128 v[80:83], v68 offset:36864
	ds_read_b128 v[84:87], v70 offset:32768
	ds_read_b128 v[88:91], v70 offset:36864
	ds_read_b128 v[92:95], v72 offset:32768
	ds_read_b128 v[96:99], v72 offset:36864
	ds_read_b128 v[100:103], v74 offset:32768
	ds_read_b128 v[144:147], v74 offset:36864
	s_waitcnt lgkmcnt(0)
	s_barrier
	v_mfma_f32_32x32x16_bf16 v[128:143], v[76:79], v[148:151], v[128:143]
	v_mfma_f32_32x32x16_bf16 v[184:199], v[76:79], v[152:155], v[184:199]
	v_mfma_f32_32x32x16_bf16 v[200:215], v[80:83], v[148:151], v[200:215]
	v_mfma_f32_32x32x16_bf16 v[216:231], v[80:83], v[152:155], v[216:231]
	v_mfma_f32_32x32x16_bf16 v[128:143], v[84:87], v[180:183], v[128:143]
	v_mfma_f32_32x32x16_bf16 v[184:199], v[84:87], v[236:239], v[184:199]
	v_mfma_f32_32x32x16_bf16 v[200:215], v[88:91], v[180:183], v[200:215]
	v_mfma_f32_32x32x16_bf16 v[216:231], v[88:91], v[236:239], v[216:231]
	v_mfma_f32_32x32x16_bf16 v[128:143], v[92:95], v[240:243], v[128:143]
	v_mfma_f32_32x32x16_bf16 v[184:199], v[92:95], v[244:247], v[184:199]
	v_mfma_f32_32x32x16_bf16 v[200:215], v[96:99], v[240:243], v[200:215]
	v_mfma_f32_32x32x16_bf16 v[216:231], v[96:99], v[244:247], v[216:231]
	v_mfma_f32_32x32x16_bf16 v[128:143], v[100:103], v[248:251], v[128:143]
	v_mfma_f32_32x32x16_bf16 v[184:199], v[100:103], v[252:255], v[184:199]
	v_mfma_f32_32x32x16_bf16 v[200:215], v[144:147], v[248:251], v[200:215]
	v_mfma_f32_32x32x16_bf16 v[216:231], v[144:147], v[252:255], v[216:231]
	s_waitcnt vmcnt(0) lgkmcnt(0)
	s_barrier
	v_readlane_b32 s8, v232, 16
	v_readlane_b32 s9, v232, 17
	v_readlane_b32 s10, v234, 2
	v_readlane_b32 s11, v234, 3
	s_nop 3
	s_and_b64 s[8:9], s[8:9], exec
	s_cselect_b32 s9, s11, s79
	s_cselect_b32 s8, s10, s78
	v_and_b32_e32 v104, 15, v156
	v_lshlrev_b32_e32 v104, 4, v104
	v_bfe_u32 v105, v156, 4, 2
	v_lshrrev_b32_e32 v106, 6, v156
	v_lshlrev_b32_e32 v106, 14, v106
	v_or_b32_e32 v107, v106, v104
	v_lshrrev_b32_e32 v66, 1, v156
	v_and_b32_e32 v66, 0xffffffc0, v66
	v_lshlrev_b32_e32 v66, 10, v66
	v_and_b32_e32 v108, 64, v156
	v_or_b32_e32 v66, v66, v108
	v_mov_b32_e32 v67, 0
	v_lshlrev_b32_e32 v108, 12, v105
	v_add_u32_e32 v110, v104, v108
	v_mov_b32_e32 v111, 0
	v_lshl_add_u64 v[68:69], s[8:9], 0, v[110:111]
	v_and_b32_e32 v109, 31, v156
	v_lshlrev_b32_e32 v109, 2, v109
	v_bfe_u32 v112, v156, 5, 1
	v_lshlrev_b32_e32 v112, 10, v112
	v_or3_b32 v125, v106, v109, v112
	v_mov_b32_e32 v70, v108
	v_mov_b32_e32 v72, v104
	v_add_u32_e32 v74, 0x4000, v108
	v_add_u32_e32 v76, 0x8000, v108
	v_add_u32_e32 v78, 0xc000, v108
	v_add_u32_e32 v80, 0x10000, v108
	v_add_u32_e32 v82, 0x14000, v108
	v_add_u32_e32 v84, 0x18000, v108
	v_add_u32_e32 v86, 0x1c000, v108
	v_add_u32_e32 v88, 0x20000, v108
	v_add_u32_e32 v90, 0x24000, v108
	v_add_u32_e32 v92, 0x28000, v108
	v_add_u32_e32 v94, 0x2c000, v108
	v_add_u32_e32 v96, 0x30000, v108
	v_add_u32_e32 v98, 0x34000, v108
	v_add_u32_e32 v100, 0x38000, v108
	v_add_u32_e32 v102, 0x3c000, v108
	v_lshl_add_u32 v109, v105, 8, v107
	v_mov_b32_e32 v144, v109
	v_add_u32_e32 v145, 0x400, v109
	v_add_u32_e32 v146, 0x800, v109
	v_add_u32_e32 v147, 0xc00, v109
	v_add_u32_e32 v148, 0x1000, v109
	v_add_u32_e32 v149, 0x1400, v109
	v_add_u32_e32 v150, 0x1800, v109
	v_add_u32_e32 v151, 0x1c00, v109
	v_add_u32_e32 v152, 0x2000, v109
	v_add_u32_e32 v153, 0x2400, v109
	v_add_u32_e32 v154, 0x2800, v109
	v_add_u32_e32 v155, 0x2c00, v109
	v_add_u32_e32 v180, 0x3000, v109
	v_add_u32_e32 v181, 0x3400, v109
	v_add_u32_e32 v182, 0x3800, v109
	v_add_u32_e32 v183, 0x3c00, v109
	s_branch .LBB0_993
